# stick-breaking loop: replace __syncthreads_and (3 barriers + DPP reduce per step) with a 1-barrier LDS marker vote
# speedup vs baseline: 1.0136x; 1.0062x over previous
.LBB0_548:
	s_andn2_b64 vcc, exec, s[0:1]
	v_readlane_b32 s29, v251, 30
	s_cbranch_vccnz .LBB0_810
	v_mov_b32_e32 v154, v144
	s_waitcnt vmcnt(0) lgkmcnt(0)
	v_cmp_eq_u32_e64 s[4:5], 0, v154
	v_readfirstlane_b32 s3, v154
	v_writelane_b32 v250, 0, 59
	v_mov_b32_e32 v2, 32
	v_cmp_eq_u32_e32 vcc, 0, v144
	s_and_saveexec_b64 s[0:1], vcc
	ds_write2_b32 v2, v1, v1 offset1:1
	ds_write_b32 v2, v1 offset:8
	s_mov_b64 exec, s[0:1]
	s_waitcnt lgkmcnt(0)
	s_barrier
	v_writelane_b32 v250, s4, 23
	s_nop 1
	v_writelane_b32 v250, s5, 24
	s_and_saveexec_b64 s[0:1], s[4:5]
	s_cbranch_execz .LBB0_553
	s_mov_b64 s[14:15], exec
	v_mbcnt_lo_u32_b32 v0, s14, 0
	v_mbcnt_hi_u32_b32 v0, s15, v0
	v_cmp_eq_u32_e32 vcc, 0, v0
	s_and_saveexec_b64 s[6:7], vcc
	s_cbranch_execz .LBB0_552
	s_bcnt1_i32_b64 s2, s[14:15]
	v_mov_b32_e32 v2, s2
	global_atomic_add v2, v1, v2, s[26:27] sc0

.LBB0_618:
	v_readlane_b32 s0, v250, 25
	v_lshlrev_b32_e32 v0, 2, v160
	v_readlane_b32 s1, v250, 26
	v_lshl_add_u64 v[172:173], s[34:35], 0, v[0:1]
	v_lshl_add_u64 v[174:175], s[64:65], 0, v[0:1]
	v_lshl_add_u64 v[164:165], s[0:1], 0, v[0:1]
	v_readlane_b32 s0, v250, 27
	v_readlane_b32 s1, v250, 28
	v_lshlrev_b32_e32 v2, 1, v160
	v_mov_b32_e32 v3, v1
	v_lshl_add_u64 v[166:167], s[0:1], 0, v[0:1]
	v_add_u32_e32 v0, s20, v216
	v_subrev_u32_e32 v151, s4, v0
	v_add_u32_e32 v0, s20, v217
	v_mov_b32_e32 v14, v1
	v_mov_b32_e32 v15, v1
	v_lshl_add_u64 v[168:169], s[92:93], 0, v[2:3]
	v_lshl_add_u64 v[170:171], s[30:31], 0, v[2:3]
	v_subrev_u32_e32 v178, s4, v0
	v_mov_b32_e32 v0, v1
	v_mov_b32_e32 v2, v1
	v_mov_b32_e32 v4, v1
	v_mov_b32_e32 v5, v1
	v_mov_b32_e32 v6, v1
	v_mov_b32_e32 v7, v1
	v_mov_b32_e32 v8, v1
	v_mov_b32_e32 v9, v1
	v_mov_b32_e32 v10, v1
	v_mov_b32_e32 v11, v1
	v_mov_b32_e32 v12, v1
	v_mov_b32_e32 v13, v1
	v_mov_b64_e32 v[30:31], v[14:15]
	v_mov_b64_e32 v[46:47], v[14:15]
	s_mov_b64 s[18:19], -1
	s_xor_b64 s[60:61], s[42:43], -1
	s_add_i32 s70, s9, -1
	s_add_i32 s53, s20, 31
	s_add_i32 s2, s12, -4
	s_sub_i32 s21, 0, s13
	s_mov_b64 s[16:17], 0
	v_mov_b32_e32 v177, 1.0
	v_mov_b32_e32 v223, 0
	s_movk_i32 s22, 0xffc0
	s_mov_b32 s3, 0
	v_mov_b32_e32 v179, v218
	s_mov_b32 s23, s4
	v_mov_b64_e32 v[28:29], v[12:13]
	v_mov_b64_e32 v[26:27], v[10:11]
	v_mov_b64_e32 v[24:25], v[8:9]
	v_mov_b64_e32 v[22:23], v[6:7]
	v_mov_b64_e32 v[20:21], v[4:5]
	v_mov_b64_e32 v[18:19], v[2:3]
	v_mov_b64_e32 v[16:17], v[0:1]
	v_mov_b64_e32 v[44:45], v[12:13]
	v_mov_b64_e32 v[42:43], v[10:11]
	v_mov_b64_e32 v[40:41], v[8:9]
	v_mov_b64_e32 v[38:39], v[6:7]
	v_mov_b64_e32 v[36:37], v[4:5]
	v_mov_b64_e32 v[34:35], v[2:3]
	v_mov_b64_e32 v[32:33], v[0:1]
	s_branch .LBB0_622
.LBB0_620:
	v_cmp_ne_u32_e32 vcc, 0, v0
	s_xor_b64 s[0:1], s[16:17], -1
	s_cbranch_vccz .LBB0_640
	s_mov_b64 s[26:27], 0x800
	s_mov_b64 s[18:19], 0
	s_cbranch_execnz .LBB0_729

.LBB0_634:
	s_lshl_b32 s0, s3, 1
	s_or_b32 s24, s0, 1
	s_mul_i32 s0, s24, 0x2400
	s_add_i32 s26, s0, 0x100
	v_readlane_b32 s0, v252, 0
	v_add3_u32 v0, s26, v206, v207
	s_mulk_i32 s24, 0x3000
	v_readlane_b32 s1, v252, 1
	s_waitcnt vmcnt(1)
	ds_write_b128 v0, v[140:143]
	s_load_dword s29, s[0:1], 0xc
	v_add_u32_e32 v0, s24, v208
	s_or_b64 s[0:1], s[16:17], s[60:61]
	s_waitcnt vmcnt(0)
	ds_write_b128 v0, v[136:139] offset:36864
	v_readlane_b32 s29, v250, 59
	s_add_i32 s50, s29, 4
	s_cmp_eq_u32 s50, 12
	s_cselect_b32 s50, 0, s50
	v_writelane_b32 v250, s50, 59
	v_mov_b32_e32 v0, s29
	v_add_u32_e32 v0, 32, v0
	v_mov_b32_e32 v2, s50
	v_add_u32_e32 v2, 32, v2
	v_cmp_eq_u32_e32 vcc, 0, v144
	s_and_saveexec_b64 s[50:51], vcc
	ds_write_b32 v2, v1
	s_mov_b64 exec, s[50:51]
	v_cmp_eq_u32_e32 vcc, 0, v199
	s_andn2_b64 vcc, vcc, s[0:1]
	s_and_saveexec_b64 s[50:51], vcc
	ds_write_b32 v0, v196
	s_mov_b64 exec, s[50:51]
	s_waitcnt lgkmcnt(0)
	s_barrier
	ds_read_b32 v0, v0
	s_waitcnt lgkmcnt(0)
	v_cmp_eq_u32_e32 vcc, 0, v0
	s_nop 1
	v_cndmask_b32_e64 v0, 0, 1, vcc
	s_branch .LBB0_620
